# norm1 and ofprep_norm: gain/scale/shift loads of a row issued together
# speedup vs baseline: 1.0089x; 1.0025x over previous
.LBB0_776:
	s_or_b64 exec, exec, s[0:1]
	v_min_i32_e32 v50, 0x8000, v32
	v_ashrrev_i32_e32 v50, 12, v50
	v_mul_i32_i24_e32 v50, 9, v50
	v_ashrrev_i32_e32 v51, 31, v50
	v_lshlrev_b64 v[50:51], 12, v[50:51]
	v_lshl_add_u64 v[80:81], v[40:41], 0, v[50:51]
	s_mov_b64 s[0:1], 0x1000
	v_lshl_add_u64 v[82:83], v[80:81], 0, s[0:1]
	s_movk_i32 s0, 0x1000
	v_add_co_u32_e32 v68, vcc, s0, v80
	global_load_dwordx4 v[50:53], v[38:39], off offset:16
	global_load_dwordx4 v[54:57], v[38:39], off
	flat_load_dwordx4 v[64:67], v[82:83] offset:16
	v_addc_co_u32_e32 v69, vcc, 0, v81, vcc
	flat_load_dwordx4 v[68:71], v[68:69]
	s_nop 0
	flat_load_dwordx4 v[72:75], v[80:81] offset:16
	flat_load_dwordx4 v[76:79], v[80:81]
	global_load_dwordx4 v[112:115], v[38:39], off offset:2048
	global_load_dwordx4 v[116:119], v[82:83], off offset:2048
	global_load_dwordx4 v[120:123], v[38:39], off offset:2064
	global_load_dwordx4 v[124:127], v[82:83], off offset:2064
	global_load_dwordx4 v[128:131], v[80:81], off offset:2048
	global_load_dwordx4 v[132:135], v[80:81], off offset:2064
	s_waitcnt vmcnt(0) lgkmcnt(0)
	v_mul_f32_e32 v63, v17, v17
	v_mul_f32_e32 v84, v25, v25
	v_fmac_f32_e32 v63, v16, v16
	v_fmac_f32_e32 v84, v24, v24
	v_fmac_f32_e32 v63, v18, v18
	v_fmac_f32_e32 v84, v26, v26
	v_fmac_f32_e32 v63, v19, v19
	v_fmac_f32_e32 v84, v27, v27
	v_add_f32_e32 v63, v84, v63
	v_mul_f32_e32 v84, v13, v13
	v_fmac_f32_e32 v84, v12, v12
	v_fmac_f32_e32 v84, v14, v14
	v_fmac_f32_e32 v84, v15, v15
	v_add_f32_e32 v63, v84, v63
	v_mul_f32_e32 v84, v29, v29
	v_fmac_f32_e32 v84, v28, v28
	v_fmac_f32_e32 v84, v30, v30
	v_fmac_f32_e32 v84, v31, v31
	v_add_f32_e32 v63, v84, v63
	ds_bpermute_b32 v84, v35, v63
	s_mov_b32 s0, 0x800000
	s_waitcnt lgkmcnt(0)
	v_add_f32_e32 v63, v63, v84
	ds_bpermute_b32 v84, v58, v63
	s_waitcnt lgkmcnt(0)
	v_add_f32_e32 v63, v63, v84
	ds_bpermute_b32 v84, v59, v63
	s_waitcnt lgkmcnt(0)
	v_add_f32_e32 v63, v63, v84
	ds_bpermute_b32 v84, v60, v63
	s_waitcnt lgkmcnt(0)
	v_add_f32_e32 v63, v63, v84
	ds_bpermute_b32 v84, v61, v63
	s_waitcnt lgkmcnt(0)
	v_add_f32_e32 v63, v63, v84
	ds_bpermute_b32 v86, v62, v63
	v_lshl_add_u64 v[84:85], v[46:47], 0, v[42:43]
	s_waitcnt lgkmcnt(0)
	v_add_f32_e32 v63, v63, v86
	v_fmamk_f32 v63, v63, 0x3a800000, v191
	v_mul_f32_e32 v86, 0x4b800000, v63
	v_cmp_gt_f32_e32 vcc, s0, v63
	s_mov_b32 s0, 0xc944000
	v_add_co_u32_e64 v84, s[0:1], s0, v84
	v_cndmask_b32_e32 v63, v63, v86, vcc
	v_rsq_f32_e32 v63, v63
	v_addc_co_u32_e64 v85, s[0:1], 0, v85, s[0:1]
	s_mov_b32 s0, 0x8800
	v_mul_f32_e32 v86, 0x45800000, v63
	v_cndmask_b32_e32 v86, v63, v86, vcc
	v_pk_mul_f32 v[18:19], v[18:19], v[86:87] op_sel_hi:[1,0]
	v_pk_mul_f32 v[16:17], v[16:17], v[86:87] op_sel_hi:[1,0]
	v_pk_mul_f32 v[26:27], v[26:27], v[86:87] op_sel_hi:[1,0]
	v_pk_mul_f32 v[24:25], v[24:25], v[86:87] op_sel_hi:[1,0]
	v_pk_mul_f32 v[14:15], v[14:15], v[86:87] op_sel_hi:[1,0]
	v_pk_mul_f32 v[12:13], v[12:13], v[86:87] op_sel_hi:[1,0]
	v_pk_mul_f32 v[24:25], v[50:51], v[24:25]
	v_pk_mul_f32 v[16:17], v[54:55], v[16:17]
	v_pk_mul_f32 v[18:19], v[56:57], v[18:19]
	v_pk_mul_f32 v[26:27], v[52:53], v[26:27]
	v_pk_add_f32 v[50:51], v[66:67], 1.0 op_sel_hi:[1,0]
	v_pk_add_f32 v[52:53], v[64:65], 1.0 op_sel_hi:[1,0]
	v_pk_add_f32 v[54:55], v[70:71], 1.0 op_sel_hi:[1,0]
	v_pk_add_f32 v[56:57], v[68:69], 1.0 op_sel_hi:[1,0]
	v_pk_fma_f32 v[26:27], v[50:51], v[26:27], v[74:75]
	v_pk_fma_f32 v[24:25], v[52:53], v[24:25], v[72:73]
	v_pk_fma_f32 v[50:51], v[54:55], v[18:19], v[78:79]
	v_pk_fma_f32 v[16:17], v[56:57], v[16:17], v[76:77]
	v_cvt_pk_bf16_f32 v18, v24, v25
	v_cvt_pk_bf16_f32 v19, v26, v27
	v_cvt_pk_bf16_f32 v16, v16, v17
	v_cvt_pk_bf16_f32 v17, v50, v51
	flat_store_dwordx4 v[84:85], v[16:19]
	s_nop 1
	v_mov_b64_e32 v[24:25], v[112:113]
	v_mov_b64_e32 v[26:27], v[114:115]
	s_nop 1
	v_mov_b64_e32 v[50:51], v[116:117]
	v_mov_b64_e32 v[52:53], v[118:119]
	s_nop 1
	v_mov_b64_e32 v[54:55], v[120:121]
	v_mov_b64_e32 v[56:57], v[122:123]
	s_nop 1
	v_mov_b64_e32 v[64:65], v[124:125]
	v_mov_b64_e32 v[66:67], v[126:127]
	s_nop 1
	v_mov_b64_e32 v[68:69], v[128:129]
	v_mov_b64_e32 v[70:71], v[130:131]
	s_nop 1
	v_mov_b64_e32 v[72:73], v[132:133]
	v_mov_b64_e32 v[74:75], v[134:135]
	v_mul_f32_e32 v16, v5, v5
	v_mul_f32_e32 v17, v9, v9
	v_mul_f32_e32 v18, v1, v1
	v_fmac_f32_e32 v16, v4, v4
	v_fmac_f32_e32 v17, v8, v8
	v_mul_f32_e32 v19, v21, v21
	v_fmac_f32_e32 v18, v0, v0
	v_fmac_f32_e32 v16, v6, v6
	v_fmac_f32_e32 v17, v10, v10
	v_fmac_f32_e32 v19, v20, v20
	v_fmac_f32_e32 v18, v2, v2
	v_fmac_f32_e32 v16, v7, v7
	v_fmac_f32_e32 v17, v11, v11
	v_fmac_f32_e32 v19, v22, v22
	v_fmac_f32_e32 v18, v3, v3
	v_add_f32_e32 v16, v17, v16
	v_fmac_f32_e32 v19, v23, v23
	v_add_f32_e32 v16, v18, v16
	v_add_f32_e32 v16, v19, v16
	ds_bpermute_b32 v17, v35, v16
	v_pk_mul_f32 v[18:19], v[30:31], v[86:87] op_sel_hi:[1,0]
	v_pk_mul_f32 v[28:29], v[28:29], v[86:87] op_sel_hi:[1,0]
	v_cmp_gt_i32_e32 vcc, s0, v33
	s_waitcnt lgkmcnt(0)
	v_add_f32_e32 v16, v16, v17
	ds_bpermute_b32 v17, v58, v16
	s_waitcnt lgkmcnt(0)
	v_add_f32_e32 v16, v16, v17
	ds_bpermute_b32 v17, v59, v16
	s_waitcnt lgkmcnt(0)
	v_add_f32_e32 v16, v16, v17
	ds_bpermute_b32 v17, v60, v16
	s_waitcnt lgkmcnt(0)
	v_add_f32_e32 v16, v16, v17
	ds_bpermute_b32 v17, v61, v16
	s_waitcnt lgkmcnt(0)
	v_add_f32_e32 v16, v16, v17
	ds_bpermute_b32 v17, v62, v16
	s_waitcnt vmcnt(0)
	v_pk_mul_f32 v[12:13], v[24:25], v[12:13]
	v_pk_mul_f32 v[14:15], v[26:27], v[14:15]
	v_pk_add_f32 v[24:25], v[52:53], 1.0 op_sel_hi:[1,0]
	v_pk_add_f32 v[26:27], v[50:51], 1.0 op_sel_hi:[1,0]
	v_pk_mul_f32 v[28:29], v[54:55], v[28:29]
	v_pk_mul_f32 v[18:19], v[56:57], v[18:19]
	v_pk_add_f32 v[30:31], v[66:67], 1.0 op_sel_hi:[1,0]
	v_pk_add_f32 v[50:51], v[64:65], 1.0 op_sel_hi:[1,0]
	v_pk_fma_f32 v[14:15], v[24:25], v[14:15], v[70:71]
	v_pk_fma_f32 v[12:13], v[26:27], v[12:13], v[68:69]
	v_pk_fma_f32 v[18:19], v[18:19], v[30:31], v[74:75]
	v_pk_fma_f32 v[24:25], v[28:29], v[50:51], v[72:73]
	v_cvt_pk_bf16_f32 v12, v12, v13
	v_cvt_pk_bf16_f32 v13, v14, v15
	v_cvt_pk_bf16_f32 v14, v24, v25
	v_cvt_pk_bf16_f32 v15, v18, v19
	flat_store_dwordx4 v[84:85], v[12:15] offset:1024
	s_and_saveexec_b64 s[48:49], vcc
	s_cbranch_execz .LBB0_771
	v_min_i32_e32 v12, 0x8000, v33
	v_ashrrev_i32_e32 v12, 12, v12
	v_mul_i32_i24_e32 v12, 9, v12
	v_ashrrev_i32_e32 v13, 31, v12
	v_lshlrev_b64 v[12:13], 12, v[12:13]
	v_lshl_add_u64 v[68:69], v[40:41], 0, v[12:13]
	s_mov_b64 s[0:1], 0x1000
	v_lshl_add_u64 v[18:19], v[68:69], 0, s[0:1]
	s_movk_i32 s0, 0x1000
	v_add_co_u32_e32 v50, vcc, s0, v68
	global_load_dwordx4 v[12:15], v[38:39], off offset:16
	global_load_dwordx4 v[24:27], v[38:39], off
	flat_load_dwordx4 v[28:31], v[18:19] offset:16
	v_addc_co_u32_e32 v51, vcc, 0, v69, vcc
	flat_load_dwordx4 v[50:53], v[50:51]
	s_nop 0
	flat_load_dwordx4 v[54:57], v[68:69] offset:16
	flat_load_dwordx4 v[64:67], v[68:69]
	global_load_dwordx4 v[144:147], v[38:39], off offset:2048
	global_load_dwordx4 v[148:151], v[18:19], off offset:2048
	global_load_dwordx4 v[152:155], v[38:39], off offset:2064
	global_load_dwordx4 v[156:159], v[18:19], off offset:2064
	global_load_dwordx4 v[160:163], v[68:69], off offset:2048
	global_load_dwordx4 v[164:167], v[68:69], off offset:2064
	s_waitcnt lgkmcnt(0)
	v_add_f32_e32 v33, v16, v17
	v_fmamk_f32 v33, v33, 0x3a800000, v191
	s_mov_b32 s0, 0x800000
	v_mul_f32_e32 v63, 0x4b800000, v33
	v_cmp_gt_f32_e32 vcc, s0, v33
	v_lshl_add_u64 v[16:17], v[44:45], 0, v[42:43]
	s_mov_b32 s0, 0xc944000
	v_cndmask_b32_e32 v33, v33, v63, vcc
	v_rsq_f32_e32 v33, v33
	v_add_co_u32_e64 v70, s[0:1], s0, v16
	v_mul_f32_e32 v16, 0x45800000, v33
	v_cndmask_b32_e32 v72, v33, v16, vcc
	v_pk_mul_f32 v[6:7], v[6:7], v[72:73] op_sel_hi:[1,0]
	v_pk_mul_f32 v[4:5], v[4:5], v[72:73] op_sel_hi:[1,0]
	v_pk_mul_f32 v[10:11], v[10:11], v[72:73] op_sel_hi:[1,0]
	v_pk_mul_f32 v[8:9], v[8:9], v[72:73] op_sel_hi:[1,0]
	v_addc_co_u32_e64 v71, s[0:1], 0, v17, s[0:1]
	v_pk_mul_f32 v[2:3], v[2:3], v[72:73] op_sel_hi:[1,0]
	v_pk_mul_f32 v[0:1], v[0:1], v[72:73] op_sel_hi:[1,0]
	v_pk_mul_f32 v[22:23], v[22:23], v[72:73] op_sel_hi:[1,0]
	v_pk_mul_f32 v[20:21], v[20:21], v[72:73] op_sel_hi:[1,0]
	s_waitcnt vmcnt(0)
	v_pk_mul_f32 v[8:9], v[8:9], v[12:13]
	v_pk_mul_f32 v[4:5], v[4:5], v[24:25]
	v_pk_mul_f32 v[6:7], v[6:7], v[26:27]
	v_pk_mul_f32 v[10:11], v[10:11], v[14:15]
	v_pk_add_f32 v[12:13], v[30:31], 1.0 op_sel_hi:[1,0]
	v_pk_add_f32 v[14:15], v[28:29], 1.0 op_sel_hi:[1,0]
	v_pk_add_f32 v[16:17], v[52:53], 1.0 op_sel_hi:[1,0]
	v_pk_add_f32 v[24:25], v[50:51], 1.0 op_sel_hi:[1,0]
	v_pk_fma_f32 v[10:11], v[10:11], v[12:13], v[56:57]
	v_pk_fma_f32 v[8:9], v[8:9], v[14:15], v[54:55]
	v_pk_fma_f32 v[12:13], v[6:7], v[16:17], v[66:67]
	v_pk_fma_f32 v[4:5], v[4:5], v[24:25], v[64:65]
	v_cvt_pk_bf16_f32 v6, v8, v9
	v_cvt_pk_bf16_f32 v7, v10, v11
	v_cvt_pk_bf16_f32 v4, v4, v5
	v_cvt_pk_bf16_f32 v5, v12, v13
	flat_store_dwordx4 v[70:71], v[4:7]
	s_nop 1
	v_mov_b64_e32 v[4:5], v[144:145]
	v_mov_b64_e32 v[6:7], v[146:147]
	s_nop 0
	s_nop 1
	v_mov_b64_e32 v[8:9], v[148:149]
	v_mov_b64_e32 v[10:11], v[150:151]
	s_nop 1
	v_mov_b64_e32 v[12:13], v[152:153]
	v_mov_b64_e32 v[14:15], v[154:155]
	s_nop 0
	s_nop 1
	v_mov_b64_e32 v[16:17], v[156:157]
	v_mov_b64_e32 v[18:19], v[158:159]
	s_nop 0
	s_nop 1
	v_mov_b64_e32 v[24:25], v[160:161]
	v_mov_b64_e32 v[26:27], v[162:163]
	s_nop 1
	v_mov_b64_e32 v[28:29], v[164:165]
	v_mov_b64_e32 v[30:31], v[166:167]
	s_waitcnt vmcnt(0)
	v_pk_mul_f32 v[0:1], v[0:1], v[4:5]
	v_pk_mul_f32 v[2:3], v[2:3], v[6:7]
	s_waitcnt lgkmcnt(0)
	v_pk_add_f32 v[4:5], v[10:11], 1.0 op_sel_hi:[1,0]
	v_pk_add_f32 v[6:7], v[8:9], 1.0 op_sel_hi:[1,0]
	v_pk_mul_f32 v[8:9], v[20:21], v[12:13]
	v_pk_mul_f32 v[10:11], v[22:23], v[14:15]
	v_pk_add_f32 v[12:13], v[18:19], 1.0 op_sel_hi:[1,0]
	v_pk_add_f32 v[14:15], v[16:17], 1.0 op_sel_hi:[1,0]
	v_pk_fma_f32 v[2:3], v[2:3], v[4:5], v[26:27]
	v_pk_fma_f32 v[0:1], v[0:1], v[6:7], v[24:25]
	v_pk_fma_f32 v[4:5], v[10:11], v[12:13], v[30:31]
	v_pk_fma_f32 v[6:7], v[8:9], v[14:15], v[28:29]
	v_cvt_pk_bf16_f32 v0, v0, v1
	v_cvt_pk_bf16_f32 v1, v2, v3
	v_cvt_pk_bf16_f32 v2, v6, v7
	v_cvt_pk_bf16_f32 v3, v4, v5
	flat_store_dwordx4 v[70:71], v[0:3] offset:1024
	s_branch .LBB0_771

.LBB0_1575:
	s_or_b64 exec, exec, s[0:1]
	s_nop 0
	v_mul_f32_e32 v32, v29, v29
	v_mul_f32_e32 v33, v25, v25
	v_fmac_f32_e32 v32, v28, v28
	v_fmac_f32_e32 v33, v24, v24
	v_fmac_f32_e32 v32, v30, v30
	v_fmac_f32_e32 v33, v26, v26
	v_fmac_f32_e32 v32, v31, v31
	v_fmac_f32_e32 v33, v27, v27
	v_add_f32_e32 v32, v32, v33
	v_mul_f32_e32 v33, v21, v21
	v_fmac_f32_e32 v33, v20, v20
	v_fmac_f32_e32 v33, v22, v22
	v_fmac_f32_e32 v33, v23, v23
	v_add_f32_e32 v32, v32, v33
	v_mul_f32_e32 v33, v17, v17
	v_fmac_f32_e32 v33, v16, v16
	v_fmac_f32_e32 v33, v18, v18
	v_fmac_f32_e32 v33, v19, v19
	v_add_f32_e32 v32, v32, v33
	v_mul_f32_e32 v33, v13, v13
	v_mul_f32_e32 v34, v9, v9
	v_fmac_f32_e32 v33, v12, v12
	v_fmac_f32_e32 v34, v8, v8
	v_fmac_f32_e32 v33, v14, v14
	v_fmac_f32_e32 v34, v10, v10
	v_fmac_f32_e32 v33, v15, v15
	v_fmac_f32_e32 v34, v11, v11
	v_add_f32_e32 v33, v33, v34
	v_mul_f32_e32 v34, v5, v5
	v_fmac_f32_e32 v34, v4, v4
	v_fmac_f32_e32 v34, v6, v6
	v_fmac_f32_e32 v34, v7, v7
	v_add_f32_e32 v33, v33, v34
	v_mul_f32_e32 v34, v1, v1
	v_fmac_f32_e32 v34, v0, v0
	v_fmac_f32_e32 v34, v2, v2
	v_fmac_f32_e32 v34, v3, v3
	v_add_f32_e32 v33, v33, v34
	ds_bpermute_b32 v34, v98, v32
	s_mov_b64 s[0:1], 0x4000
	global_load_dwordx4 v[42:45], v[74:75], off offset:16
	global_load_dwordx4 v[46:49], v[74:75], off
	v_lshlrev_b64 v[38:39], 11, v[84:85]
	s_waitcnt lgkmcnt(0)
	v_add_f32_e32 v32, v32, v34
	ds_bpermute_b32 v34, v98, v33
	s_waitcnt lgkmcnt(0)
	v_add_f32_e32 v33, v33, v34
	ds_bpermute_b32 v34, v99, v32
	s_waitcnt lgkmcnt(0)
	v_add_f32_e32 v32, v32, v34
	ds_bpermute_b32 v34, v99, v33
	s_waitcnt lgkmcnt(0)
	v_add_f32_e32 v33, v33, v34
	ds_bpermute_b32 v34, v97, v32
	s_waitcnt lgkmcnt(0)
	v_add_f32_e32 v32, v32, v34
	ds_bpermute_b32 v34, v97, v33
	s_waitcnt lgkmcnt(0)
	v_add_f32_e32 v33, v33, v34
	ds_bpermute_b32 v34, v96, v32
	s_waitcnt lgkmcnt(0)
	v_add_f32_e32 v32, v32, v34
	ds_bpermute_b32 v34, v96, v33
	s_waitcnt lgkmcnt(0)
	v_add_f32_e32 v33, v33, v34
	ds_bpermute_b32 v34, v95, v32
	s_waitcnt lgkmcnt(0)
	v_add_f32_e32 v32, v32, v34
	ds_bpermute_b32 v34, v95, v33
	s_waitcnt lgkmcnt(0)
	v_add_f32_e32 v33, v33, v34
	ds_bpermute_b32 v34, v94, v32
	ds_bpermute_b32 v40, v94, v33
	s_waitcnt lgkmcnt(0)
	v_add_f32_e32 v32, v32, v34
	v_fmamk_f32 v32, v32, 0x3a800000, v191
	v_cmp_gt_f32_e32 vcc, s81, v32
	v_mul_f32_e32 v36, 0x4b800000, v32
	v_min_i32_e32 v34, 0x8000, v84
	v_cndmask_b32_e32 v32, v32, v36, vcc
	v_ashrrev_i32_e32 v34, 12, v34
	v_rsq_f32_e32 v32, v32
	v_mul_i32_i24_e32 v34, 9, v34
	v_ashrrev_i32_e32 v35, 31, v34
	v_lshlrev_b64 v[34:35], 12, v[34:35]
	v_mul_f32_e32 v36, 0x45800000, v32
	v_lshl_add_u64 v[54:55], v[78:79], 0, v[34:35]
	v_cndmask_b32_e32 v32, v32, v36, vcc
	v_lshl_add_u64 v[36:37], v[54:55], 0, s[0:1]
	s_mov_b64 s[0:1], 0x3000
	v_lshl_add_u64 v[34:35], v[54:55], 0, s[0:1]
	s_movk_i32 s0, 0x4000
	v_add_co_u32_e32 v50, vcc, s0, v54
	s_movk_i32 s0, 0x3000
	s_nop 0
	v_addc_co_u32_e32 v51, vcc, 0, v55, vcc
	v_add_co_u32_e32 v54, vcc, s0, v54
	flat_load_dwordx4 v[50:53], v[50:51]
	s_nop 0
	v_addc_co_u32_e32 v55, vcc, 0, v55, vcc
	flat_load_dwordx4 v[54:57], v[54:55]
	global_load_dwordx4 v[112:115], v[36:37], off offset:16
	global_load_dwordx4 v[116:119], v[34:35], off offset:16
	global_load_dwordx4 v[120:123], v[76:77], off offset:16
	global_load_dwordx4 v[124:127], v[76:77], off
	global_load_dwordx4 v[128:131], v[36:37], off offset:2048
	global_load_dwordx4 v[132:135], v[34:35], off offset:2048
	global_load_dwordx4 v[136:139], v[36:37], off offset:2064
	global_load_dwordx4 v[140:143], v[34:35], off offset:2064
	v_pk_mul_f32 v[30:31], v[30:31], v[32:33] op_sel_hi:[1,0]
	v_pk_mul_f32 v[28:29], v[28:29], v[32:33] op_sel_hi:[1,0]
	s_waitcnt vmcnt(0)
	v_pk_mul_f32 v[30:31], v[48:49], v[30:31]
	v_pk_mul_f32 v[28:29], v[46:47], v[28:29]
	v_pk_mul_f32 v[26:27], v[26:27], v[32:33] op_sel_hi:[1,0]
	v_pk_mul_f32 v[24:25], v[24:25], v[32:33] op_sel_hi:[1,0]
	v_pk_mul_f32 v[26:27], v[44:45], v[26:27]
	v_pk_mul_f32 v[24:25], v[42:43], v[24:25]
	v_pk_mul_f32 v[22:23], v[22:23], v[32:33] op_sel_hi:[1,0]
	v_pk_mul_f32 v[20:21], v[20:21], v[32:33] op_sel_hi:[1,0]
	v_pk_mul_f32 v[18:19], v[18:19], v[32:33] op_sel_hi:[1,0]
	v_pk_mul_f32 v[16:17], v[16:17], v[32:33] op_sel_hi:[1,0]
	s_mov_b32 s0, 0x8800
	v_cmp_gt_i32_e32 vcc, s0, v82
	s_waitcnt lgkmcnt(0)
	v_pk_add_f32 v[46:47], v[52:53], 1.0 op_sel_hi:[1,0]
	v_pk_add_f32 v[48:49], v[50:51], 1.0 op_sel_hi:[1,0]
	v_pk_fma_f32 v[50:51], v[46:47], v[30:31], v[56:57]
	v_pk_fma_f32 v[52:53], v[48:49], v[28:29], v[54:55]
	s_nop 1
	v_mov_b64_e32 v[28:29], v[112:113]
	v_mov_b64_e32 v[30:31], v[114:115]
	s_nop 1
	v_mov_b64_e32 v[46:47], v[116:117]
	v_mov_b64_e32 v[48:49], v[118:119]
	s_waitcnt vmcnt(0) lgkmcnt(0)
	v_pk_add_f32 v[30:31], v[30:31], 1.0 op_sel_hi:[1,0]
	v_pk_add_f32 v[28:29], v[28:29], 1.0 op_sel_hi:[1,0]
	v_pk_fma_f32 v[30:31], v[30:31], v[26:27], v[48:49]
	v_pk_fma_f32 v[26:27], v[28:29], v[24:25], v[46:47]
	v_cvt_pk_bf16_f32 v24, v52, v53
	v_cvt_pk_bf16_f32 v25, v50, v51
	v_cvt_pk_bf16_f32 v26, v26, v27
	v_cvt_pk_bf16_f32 v27, v30, v31
	v_lshl_add_u64 v[28:29], v[80:81], 0, v[38:39]
	flat_store_dwordx4 v[28:29], v[24:27]
	s_nop 1
	v_mov_b64_e32 v[24:25], v[120:121]
	v_mov_b64_e32 v[26:27], v[122:123]
	s_nop 0
	s_nop 1
	v_mov_b64_e32 v[42:43], v[124:125]
	v_mov_b64_e32 v[44:45], v[126:127]
	s_nop 1
	v_mov_b64_e32 v[46:47], v[128:129]
	v_mov_b64_e32 v[48:49], v[130:131]
	s_nop 1
	v_mov_b64_e32 v[50:51], v[132:133]
	v_mov_b64_e32 v[52:53], v[134:135]
	s_waitcnt vmcnt(0)
	v_pk_mul_f32 v[16:17], v[24:25], v[16:17]
	v_pk_mul_f32 v[20:21], v[42:43], v[20:21]
	v_pk_mul_f32 v[22:23], v[44:45], v[22:23]
	s_waitcnt lgkmcnt(0)
	v_pk_add_f32 v[30:31], v[48:49], 1.0 op_sel_hi:[1,0]
	v_pk_add_f32 v[38:39], v[46:47], 1.0 op_sel_hi:[1,0]
	v_pk_fma_f32 v[30:31], v[30:31], v[22:23], v[52:53]
	v_pk_fma_f32 v[38:39], v[38:39], v[20:21], v[50:51]
	s_nop 1
	v_mov_b64_e32 v[20:21], v[136:137]
	v_mov_b64_e32 v[22:23], v[138:139]
	s_nop 0
	s_nop 1
	v_mov_b64_e32 v[34:35], v[140:141]
	v_mov_b64_e32 v[36:37], v[142:143]
	v_pk_mul_f32 v[18:19], v[26:27], v[18:19]
	s_waitcnt vmcnt(0) lgkmcnt(0)
	v_pk_add_f32 v[22:23], v[22:23], 1.0 op_sel_hi:[1,0]
	v_pk_add_f32 v[20:21], v[20:21], 1.0 op_sel_hi:[1,0]
	v_pk_fma_f32 v[22:23], v[18:19], v[22:23], v[36:37]
	v_pk_fma_f32 v[18:19], v[16:17], v[20:21], v[34:35]
	v_cvt_pk_bf16_f32 v16, v38, v39
	v_cvt_pk_bf16_f32 v17, v30, v31
	v_cvt_pk_bf16_f32 v18, v18, v19
	v_cvt_pk_bf16_f32 v19, v22, v23
	flat_store_dwordx4 v[28:29], v[16:19] offset:1024
	s_and_saveexec_b64 s[0:1], vcc
	s_cbranch_execz .LBB0_1572
	v_min_i32_e32 v16, 0x8000, v82
	v_ashrrev_i32_e32 v16, 12, v16
	v_mul_i32_i24_e32 v16, 9, v16
	v_add_f32_e32 v20, v33, v40
	v_ashrrev_i32_e32 v17, 31, v16
	v_lshlrev_b64 v[18:19], 12, v[16:17]
	v_fmamk_f32 v16, v20, 0x3a800000, v191
	v_cmp_gt_f32_e32 vcc, s81, v16
	v_mul_f32_e32 v17, 0x4b800000, v16
	v_lshl_add_u64 v[34:35], v[78:79], 0, v[18:19]
	v_cndmask_b32_e32 v16, v16, v17, vcc
	v_rsq_f32_e32 v16, v16
	s_movk_i32 s30, 0x4000
	s_mov_b64 s[42:43], 0x4000
	v_lshl_add_u64 v[20:21], v[34:35], 0, s[42:43]
	v_mul_f32_e32 v17, 0x45800000, v16
	v_cndmask_b32_e32 v16, v16, v17, vcc
	v_add_co_u32_e32 v30, vcc, s30, v34
	s_mov_b64 s[42:43], 0x3000
	s_nop 0
	v_addc_co_u32_e32 v31, vcc, 0, v35, vcc
	s_movk_i32 s30, 0x3000
	v_lshl_add_u64 v[18:19], v[34:35], 0, s[42:43]
	v_add_co_u32_e32 v34, vcc, s30, v34
	global_load_dwordx4 v[22:25], v[74:75], off offset:16
	global_load_dwordx4 v[26:29], v[74:75], off
	v_addc_co_u32_e32 v35, vcc, 0, v35, vcc
	flat_load_dwordx4 v[30:33], v[30:31]
	v_pk_mul_f32 v[14:15], v[14:15], v[16:17] op_sel_hi:[1,0]
	flat_load_dwordx4 v[34:37], v[34:35]
	global_load_dwordx4 v[144:147], v[20:21], off offset:16
	global_load_dwordx4 v[148:151], v[18:19], off offset:16
	global_load_dwordx4 v[152:155], v[76:77], off offset:16
	global_load_dwordx4 v[156:159], v[76:77], off
	global_load_dwordx4 v[160:163], v[20:21], off offset:2048
	global_load_dwordx4 v[164:167], v[18:19], off offset:2048
	global_load_dwordx4 v[168:171], v[20:21], off offset:2064
	global_load_dwordx4 v[172:175], v[18:19], off offset:2064
	v_pk_mul_f32 v[12:13], v[12:13], v[16:17] op_sel_hi:[1,0]
	v_pk_mul_f32 v[10:11], v[10:11], v[16:17] op_sel_hi:[1,0]
	v_pk_mul_f32 v[8:9], v[8:9], v[16:17] op_sel_hi:[1,0]
	v_lshlrev_b64 v[38:39], 11, v[82:83]
	v_pk_mul_f32 v[6:7], v[6:7], v[16:17] op_sel_hi:[1,0]
	v_pk_mul_f32 v[4:5], v[4:5], v[16:17] op_sel_hi:[1,0]
	v_pk_mul_f32 v[2:3], v[2:3], v[16:17] op_sel_hi:[1,0]
	v_pk_mul_f32 v[0:1], v[0:1], v[16:17] op_sel_hi:[1,0]
	s_waitcnt vmcnt(0)
	v_pk_mul_f32 v[8:9], v[8:9], v[22:23]
	v_pk_mul_f32 v[12:13], v[12:13], v[26:27]
	v_pk_mul_f32 v[14:15], v[14:15], v[28:29]
	v_pk_mul_f32 v[10:11], v[10:11], v[24:25]
	s_waitcnt lgkmcnt(0)
	v_pk_add_f32 v[26:27], v[32:33], 1.0 op_sel_hi:[1,0]
	v_pk_add_f32 v[28:29], v[30:31], 1.0 op_sel_hi:[1,0]
	v_pk_fma_f32 v[30:31], v[14:15], v[26:27], v[36:37]
	v_pk_fma_f32 v[32:33], v[12:13], v[28:29], v[34:35]
	s_nop 1
	v_mov_b64_e32 v[12:13], v[144:145]
	v_mov_b64_e32 v[14:15], v[146:147]
	s_nop 1
	v_mov_b64_e32 v[26:27], v[148:149]
	v_mov_b64_e32 v[28:29], v[150:151]
	s_waitcnt vmcnt(0) lgkmcnt(0)
	v_pk_add_f32 v[14:15], v[14:15], 1.0 op_sel_hi:[1,0]
	v_pk_add_f32 v[12:13], v[12:13], 1.0 op_sel_hi:[1,0]
	v_pk_fma_f32 v[14:15], v[10:11], v[14:15], v[28:29]
	v_pk_fma_f32 v[10:11], v[8:9], v[12:13], v[26:27]
	v_cvt_pk_bf16_f32 v8, v32, v33
	v_cvt_pk_bf16_f32 v9, v30, v31
	v_cvt_pk_bf16_f32 v10, v10, v11
	v_cvt_pk_bf16_f32 v11, v14, v15
	v_lshl_add_u64 v[30:31], v[80:81], 0, v[38:39]
	flat_store_dwordx4 v[30:31], v[8:11]
	s_nop 1
	v_mov_b64_e32 v[8:9], v[152:153]
	v_mov_b64_e32 v[10:11], v[154:155]
	s_nop 0
	s_nop 1
	v_mov_b64_e32 v[12:13], v[156:157]
	v_mov_b64_e32 v[14:15], v[158:159]
	s_nop 1
	v_mov_b64_e32 v[22:23], v[160:161]
	v_mov_b64_e32 v[24:25], v[162:163]
	s_nop 1
	v_mov_b64_e32 v[26:27], v[164:165]
	v_mov_b64_e32 v[28:29], v[166:167]
	s_waitcnt vmcnt(0)
	v_pk_mul_f32 v[0:1], v[0:1], v[8:9]
	v_pk_mul_f32 v[4:5], v[4:5], v[12:13]
	v_pk_mul_f32 v[6:7], v[6:7], v[14:15]
	s_waitcnt lgkmcnt(0)
	v_pk_add_f32 v[12:13], v[24:25], 1.0 op_sel_hi:[1,0]
	v_pk_add_f32 v[14:15], v[22:23], 1.0 op_sel_hi:[1,0]
	v_pk_fma_f32 v[22:23], v[6:7], v[12:13], v[28:29]
	v_pk_fma_f32 v[24:25], v[4:5], v[14:15], v[26:27]
	s_nop 1
	v_mov_b64_e32 v[4:5], v[168:169]
	v_mov_b64_e32 v[6:7], v[170:171]
	s_nop 1
	v_mov_b64_e32 v[12:13], v[172:173]
	v_mov_b64_e32 v[14:15], v[174:175]
	v_pk_mul_f32 v[2:3], v[2:3], v[10:11]
	s_waitcnt vmcnt(0) lgkmcnt(0)
	v_pk_add_f32 v[6:7], v[6:7], 1.0 op_sel_hi:[1,0]
	v_pk_add_f32 v[4:5], v[4:5], 1.0 op_sel_hi:[1,0]
	v_pk_fma_f32 v[6:7], v[2:3], v[6:7], v[14:15]
	v_pk_fma_f32 v[2:3], v[0:1], v[4:5], v[12:13]
	v_cvt_pk_bf16_f32 v0, v24, v25
	v_cvt_pk_bf16_f32 v1, v22, v23
	v_cvt_pk_bf16_f32 v2, v2, v3
	v_cvt_pk_bf16_f32 v3, v6, v7
	flat_store_dwordx4 v[30:31], v[0:3] offset:1024
	s_branch .LBB0_1572
